# tile-header scratch VGPR renamed off the accumulator registers (no write-after-store-read on the epilogue's last store)
# baseline (speedup 1.0000x reference)
.LBB0_196:
	s_add_i32 s70, s70, 1
	s_mul_i32 s10, s70, s73
	s_mul_hi_u32 s11, s70, s66
	s_add_i32 s11, s11, s10
	s_mul_i32 s10, s70, s66
	s_add_u32 s10, s10, s2
	s_addc_u32 s11, s11, s67
	v_cmp_gt_i64_e64 s[40:41], s[10:11], v[150:151]
	v_cmp_lt_i64_e64 s[42:43], s[10:11], v[148:149]
	s_and_b64 vcc, exec, s[40:41]
	s_cbranch_vccnz .LBB0_198
	s_ashr_i32 s11, s10, 31
	s_lshr_b32 s11, s11, 29
	s_add_i32 s11, s10, s11
	s_ashr_i32 s28, s11, 3
	s_and_b32 s11, s11, -8
	s_sub_i32 s10, s10, s11
	s_cmp_lt_i32 s10, 0
	s_movk_i32 s11, 0x2c1
	s_cselect_b32 s11, s11, 0x2c0
	s_mul_i32 s10, s10, s11
	s_add_i32 s10, s10, s28
	s_mul_hi_i32 s11, s10, 0x2e8ba2e9
	s_lshr_b32 s28, s11, 31
	s_ashr_i32 s11, s11, 4
	s_add_i32 s11, s11, s28
	s_lshl_b32 s28, s11, 2
	s_sub_i32 s29, 0x100, s28
	s_min_i32 s29, s29, 4
	s_abs_i32 s44, s29
	v_cvt_f32_u32_e32 v255, s44
	s_sub_i32 s52, 0, s44
	s_mulk_i32 s11, 0x58
	s_sub_i32 s10, s10, s11
	v_rcp_iflag_f32_e32 v255, v255
	s_abs_i32 s11, s10
	s_xor_b32 s45, s10, s29
	s_ashr_i32 s45, s45, 31
	v_mul_f32_e32 v255, 0x4f7ffffe, v255
	v_cvt_u32_f32_e32 v255, v255
	s_nop 0
	v_readfirstlane_b32 s53, v255
	s_mul_i32 s52, s52, s53
	s_mul_hi_u32 s52, s53, s52
	s_add_i32 s53, s53, s52
	s_mul_hi_u32 s52, s11, s53
	s_mul_i32 s53, s52, s44
	s_sub_i32 s11, s11, s53
	s_add_i32 s71, s52, 1
	s_sub_i32 s53, s11, s44
	s_cmp_ge_u32 s11, s44
	s_cselect_b32 s52, s71, s52
	s_cselect_b32 s11, s53, s11
	s_add_i32 s53, s52, 1
	s_cmp_ge_u32 s11, s44
	s_cselect_b32 s11, s53, s52
	s_xor_b32 s11, s11, s45
	s_sub_i32 s71, s11, s45
	s_mul_i32 s11, s71, s29
	s_sub_i32 s10, s10, s11
	s_add_i32 s89, s28, s10
.LBB0_198:
	v_cndmask_b32_e64 v255, 0, 1, s[42:43]
	v_cmp_ne_u32_e64 s[44:45], 1, v255
	s_andn2_b64 vcc, exec, s[42:43]
	s_mov_b64 s[42:43], s[8:9]
	s_cbranch_vccnz .LBB0_200
	s_ashr_i32 s10, s89, 31
	s_mul_hi_u32 s11, s48, s89
	s_mul_i32 s10, s48, s10
	s_add_i32 s10, s11, s10
	s_mul_i32 s11, s49, s89
	s_add_i32 s10, s10, s11
	s_mul_i32 s11, s48, s89
	s_add_u32 s42, s20, s11
	s_addc_u32 s43, s21, s10

.LBB0_270:
	s_ashr_i32 s10, s28, 3
	s_add_i32 s10, s46, s10
	s_ashr_i32 s11, s10, 31
	s_lshr_b32 s11, s11, 28
	s_add_i32 s11, s10, s11
	s_ashr_i32 s28, s11, 4
	s_lshl_b32 s28, s28, 2
	s_sub_i32 s29, 0x100, s28
	s_min_i32 s29, s29, 4
	s_abs_i32 s46, s29
	v_cvt_f32_u32_e32 v255, s46
	s_sub_i32 s50, 0, s46
	s_and_b32 s11, s11, -16
	s_sub_i32 s10, s10, s11
	v_rcp_iflag_f32_e32 v255, v255
	s_abs_i32 s11, s10
	s_xor_b32 s47, s10, s29
	s_ashr_i32 s47, s47, 31
	v_mul_f32_e32 v255, 0x4f7ffffe, v255
	v_cvt_u32_f32_e32 v255, v255
	s_nop 0
	v_readfirstlane_b32 s51, v255
	s_mul_i32 s50, s50, s51
	s_mul_hi_u32 s50, s51, s50
	s_add_i32 s51, s51, s50
	s_mul_hi_u32 s50, s11, s51
	s_mul_i32 s51, s50, s46
	s_sub_i32 s11, s11, s51
	s_add_i32 s69, s50, 1
	s_sub_i32 s51, s11, s46
	s_cmp_ge_u32 s11, s46
	s_cselect_b32 s50, s69, s50
	s_cselect_b32 s11, s51, s11
	s_add_i32 s51, s50, 1
	s_cmp_ge_u32 s11, s46
	s_cselect_b32 s11, s51, s50
	s_xor_b32 s11, s11, s47
	s_sub_i32 s69, s11, s47
	s_mul_i32 s11, s69, s29
	s_sub_i32 s10, s10, s11
	s_add_i32 s70, s28, s10
.LBB0_271:
	v_cndmask_b32_e64 v255, 0, 1, s[44:45]
	v_cmp_ne_u32_e64 s[46:47], 1, v255
	s_andn2_b64 vcc, exec, s[44:45]
	s_mov_b64 s[44:45], s[8:9]
	s_cbranch_vccnz .LBB0_273
	s_ashr_i32 s10, s70, 31
	s_mul_hi_u32 s11, s40, s70
	s_mul_i32 s10, s40, s10
	s_add_i32 s10, s11, s10
	s_mul_i32 s11, s41, s70
	s_add_i32 s10, s10, s11
	s_mul_i32 s11, s40, s70
	s_add_u32 s44, s20, s11
	s_addc_u32 s45, s21, s10

.LBB0_398:
	s_ashr_i32 s10, s28, 3
	s_add_i32 s10, s46, s10
	s_ashr_i32 s11, s10, 31
	s_lshr_b32 s11, s11, 28
	s_add_i32 s11, s10, s11
	s_ashr_i32 s28, s11, 4
	s_lshl_b32 s28, s28, 2
	s_sub_i32 s29, 0x100, s28
	s_min_i32 s29, s29, 4
	s_abs_i32 s46, s29
	v_cvt_f32_u32_e32 v255, s46
	s_sub_i32 s48, 0, s46
	s_and_b32 s11, s11, -16
	s_sub_i32 s10, s10, s11
	v_rcp_iflag_f32_e32 v255, v255
	s_abs_i32 s11, s10
	s_xor_b32 s47, s10, s29
	s_ashr_i32 s47, s47, 31
	v_mul_f32_e32 v255, 0x4f7ffffe, v255
	v_cvt_u32_f32_e32 v255, v255
	s_nop 0
	v_readfirstlane_b32 s49, v255
	s_mul_i32 s48, s48, s49
	s_mul_hi_u32 s48, s49, s48
	s_add_i32 s49, s49, s48
	s_mul_hi_u32 s48, s11, s49
	s_mul_i32 s49, s48, s46
	s_sub_i32 s11, s11, s49
	s_add_i32 s61, s48, 1
	s_sub_i32 s49, s11, s46
	s_cmp_ge_u32 s11, s46
	s_cselect_b32 s48, s61, s48
	s_cselect_b32 s11, s49, s11
	s_add_i32 s49, s48, 1
	s_cmp_ge_u32 s11, s46
	s_cselect_b32 s11, s49, s48
	s_xor_b32 s11, s11, s47
	s_sub_i32 s61, s11, s47
	s_mul_i32 s11, s61, s29
	s_sub_i32 s10, s10, s11
	s_add_i32 s68, s28, s10
.LBB0_399:
	v_cndmask_b32_e64 v255, 0, 1, s[44:45]
	v_cmp_ne_u32_e64 s[46:47], 1, v255
	s_andn2_b64 vcc, exec, s[44:45]
	s_mov_b64 s[44:45], s[8:9]
	s_cbranch_vccnz .LBB0_401
	s_ashr_i32 s10, s68, 31
	s_mul_hi_u32 s11, s38, s68
	s_mul_i32 s10, s38, s10
	s_add_i32 s10, s11, s10
	s_mul_i32 s11, s39, s68
	s_add_i32 s10, s10, s11
	s_mul_i32 s11, s38, s68
	s_add_u32 s44, s20, s11
	s_addc_u32 s45, s21, s10

.LBB0_419:
	s_ashr_i32 s10, s28, 3
	s_add_i32 s10, s46, s10
	s_ashr_i32 s11, s10, 31
	s_lshr_b32 s11, s11, 22
	s_add_i32 s11, s10, s11
	s_ashr_i32 s28, s11, 10
	s_lshl_b32 s28, s28, 2
	s_sub_i32 s29, 8, s28
	s_min_i32 s29, s29, 4
	s_abs_i32 s46, s29
	v_cvt_f32_u32_e32 v255, s46
	s_sub_i32 s48, 0, s46
	s_and_b32 s11, s11, 0xfffffc00
	s_sub_i32 s10, s10, s11
	v_rcp_iflag_f32_e32 v255, v255
	s_abs_i32 s11, s10
	s_xor_b32 s47, s10, s29
	s_ashr_i32 s47, s47, 31
	v_mul_f32_e32 v255, 0x4f7ffffe, v255
	v_cvt_u32_f32_e32 v255, v255
	s_nop 0
	v_readfirstlane_b32 s49, v255
	s_mul_i32 s48, s48, s49
	s_mul_hi_u32 s48, s49, s48
	s_add_i32 s49, s49, s48
	s_mul_hi_u32 s48, s11, s49
	s_mul_i32 s49, s48, s46
	s_sub_i32 s11, s11, s49
	s_add_i32 s61, s48, 1
	s_sub_i32 s49, s11, s46
	s_cmp_ge_u32 s11, s46
	s_cselect_b32 s48, s61, s48
	s_cselect_b32 s11, s49, s11
	s_add_i32 s49, s48, 1
	s_cmp_ge_u32 s11, s46
	s_cselect_b32 s11, s49, s48
	s_xor_b32 s11, s11, s47
	s_sub_i32 s61, s11, s47
	s_mul_i32 s11, s61, s29
	s_sub_i32 s10, s10, s11
	s_add_i32 s68, s28, s10

.LBB0_1051:
	s_add_i32 s60, s60, 1
	s_mul_i32 s10, s60, s73
	s_mul_hi_u32 s11, s60, s66
	s_add_i32 s11, s11, s10
	s_mul_i32 s10, s60, s66
	s_add_u32 s10, s10, s2
	s_addc_u32 s11, s11, s67
	v_cmp_gt_i64_e64 s[38:39], s[10:11], v[150:151]
	v_cmp_lt_i64_e64 s[42:43], s[10:11], v[148:149]
	s_and_b64 vcc, exec, s[38:39]
	s_cbranch_vccnz .LBB0_1053
	s_ashr_i32 s11, s10, 31
	s_lshr_b32 s11, s11, 29
	s_add_i32 s11, s10, s11
	s_ashr_i32 s28, s11, 3
	s_and_b32 s11, s11, -8
	s_sub_i32 s10, s10, s11
	s_cmp_lt_i32 s10, 0
	s_movk_i32 s11, 0x2c1
	s_cselect_b32 s11, s11, 0x2c0
	s_mul_i32 s10, s10, s11
	s_add_i32 s10, s10, s28
	s_mul_hi_i32 s11, s10, 0x2e8ba2e9
	s_lshr_b32 s28, s11, 31
	s_ashr_i32 s11, s11, 4
	s_add_i32 s11, s11, s28
	s_lshl_b32 s28, s11, 2
	s_sub_i32 s29, 0x100, s28
	s_min_i32 s29, s29, 4
	s_abs_i32 s44, s29
	v_cvt_f32_u32_e32 v255, s44
	s_sub_i32 s48, 0, s44
	s_mulk_i32 s11, 0x58
	s_sub_i32 s10, s10, s11
	v_rcp_iflag_f32_e32 v255, v255
	s_abs_i32 s11, s10
	s_xor_b32 s45, s10, s29
	s_ashr_i32 s45, s45, 31
	v_mul_f32_e32 v255, 0x4f7ffffe, v255
	v_cvt_u32_f32_e32 v255, v255
	s_nop 0
	v_readfirstlane_b32 s49, v255
	s_mul_i32 s48, s48, s49
	s_mul_hi_u32 s48, s49, s48
	s_add_i32 s49, s49, s48
	s_mul_hi_u32 s48, s11, s49
	s_mul_i32 s49, s48, s44
	s_sub_i32 s11, s11, s49
	s_add_i32 s61, s48, 1
	s_sub_i32 s49, s11, s44
	s_cmp_ge_u32 s11, s44
	s_cselect_b32 s48, s61, s48
	s_cselect_b32 s11, s49, s11
	s_add_i32 s49, s48, 1
	s_cmp_ge_u32 s11, s44
	s_cselect_b32 s11, s49, s48
	s_xor_b32 s11, s11, s45
	s_sub_i32 s61, s11, s45
	s_mul_i32 s11, s61, s29
	s_sub_i32 s10, s10, s11
	s_add_i32 s68, s28, s10
.LBB0_1053:
	v_cndmask_b32_e64 v255, 0, 1, s[42:43]
	v_cmp_ne_u32_e64 s[44:45], 1, v255
	s_andn2_b64 vcc, exec, s[42:43]
	s_mov_b64 s[42:43], s[8:9]
	s_cbranch_vccnz .LBB0_1055
	s_ashr_i32 s10, s68, 31
	s_mul_hi_u32 s11, s40, s68
	s_mul_i32 s10, s40, s10
	s_add_i32 s10, s11, s10
	s_mul_i32 s11, s41, s68
	s_add_i32 s10, s10, s11
	s_mul_i32 s11, s40, s68
	s_add_u32 s42, s20, s11
	s_addc_u32 s43, s21, s10

.LBB0_1125:
	s_ashr_i32 s10, s28, 3
	s_add_i32 s10, s42, s10
	s_ashr_i32 s11, s10, 31
	s_lshr_b32 s11, s11, 28
	s_add_i32 s11, s10, s11
	s_ashr_i32 s28, s11, 4
	s_lshl_b32 s28, s28, 2
	s_sub_i32 s29, 0x100, s28
	s_min_i32 s29, s29, 4
	s_abs_i32 s42, s29
	v_cvt_f32_u32_e32 v255, s42
	s_sub_i32 s48, 0, s42
	s_and_b32 s11, s11, -16
	s_sub_i32 s10, s10, s11
	v_rcp_iflag_f32_e32 v255, v255
	s_abs_i32 s11, s10
	s_xor_b32 s43, s10, s29
	s_ashr_i32 s43, s43, 31
	v_mul_f32_e32 v255, 0x4f7ffffe, v255
	v_cvt_u32_f32_e32 v255, v255
	s_nop 0
	v_readfirstlane_b32 s49, v255
	s_mul_i32 s48, s48, s49
	s_mul_hi_u32 s48, s49, s48
	s_add_i32 s49, s49, s48
	s_mul_hi_u32 s48, s11, s49
	s_mul_i32 s49, s48, s42
	s_sub_i32 s11, s11, s49
	s_add_i32 s61, s48, 1
	s_sub_i32 s49, s11, s42
	s_cmp_ge_u32 s11, s42
	s_cselect_b32 s48, s61, s48
	s_cselect_b32 s11, s49, s11
	s_add_i32 s49, s48, 1
	s_cmp_ge_u32 s11, s42
	s_cselect_b32 s11, s49, s48
	s_xor_b32 s11, s11, s43
	s_sub_i32 s61, s11, s43
	s_mul_i32 s11, s61, s29
	s_sub_i32 s10, s10, s11
	s_add_i32 s68, s28, s10
.LBB0_1126:
	v_cndmask_b32_e64 v255, 0, 1, s[40:41]
	v_cmp_ne_u32_e64 s[42:43], 1, v255
	s_andn2_b64 vcc, exec, s[40:41]
	s_mov_b64 s[40:41], s[8:9]
	s_cbranch_vccnz .LBB0_1128
	s_ashr_i32 s10, s68, 31
	s_mul_hi_u32 s11, s46, s68
	s_mul_i32 s10, s46, s10
	s_add_i32 s10, s11, s10
	s_mul_i32 s11, s47, s68
	s_add_i32 s10, s10, s11
	s_mul_i32 s11, s46, s68
	s_add_u32 s40, s20, s11
	s_addc_u32 s41, s21, s10

	.amdhsa_kernel _Z4mega6Params
		.amdhsa_group_segment_fixed_size 0
		.amdhsa_private_segment_fixed_size 0
		.amdhsa_kernarg_size 528
		.amdhsa_user_sgpr_count 2
		.amdhsa_user_sgpr_dispatch_ptr 0
		.amdhsa_user_sgpr_queue_ptr 0
		.amdhsa_user_sgpr_kernarg_segment_ptr 1
		.amdhsa_user_sgpr_dispatch_id 0
		.amdhsa_user_sgpr_kernarg_preload_length 0
		.amdhsa_user_sgpr_kernarg_preload_offset 0
		.amdhsa_user_sgpr_private_segment_size 0
		.amdhsa_uses_dynamic_stack 0
		.amdhsa_enable_private_segment 0
		.amdhsa_system_sgpr_workgroup_id_x 1
		.amdhsa_system_sgpr_workgroup_id_y 0
		.amdhsa_system_sgpr_workgroup_id_z 0
		.amdhsa_system_sgpr_workgroup_info 0
		.amdhsa_system_vgpr_workitem_id 2
		.amdhsa_next_free_vgpr 256
		.amdhsa_next_free_sgpr 100
		.amdhsa_accum_offset 256
		.amdhsa_reserve_vcc 1
		.amdhsa_float_round_mode_32 0
		.amdhsa_float_round_mode_16_64 0
		.amdhsa_float_denorm_mode_32 3
		.amdhsa_float_denorm_mode_16_64 3
		.amdhsa_dx10_clamp 1
		.amdhsa_ieee_mode 1
		.amdhsa_fp16_overflow 0
		.amdhsa_tg_split 0
		.amdhsa_exception_fp_ieee_invalid_op 0
		.amdhsa_exception_fp_denorm_src 0
		.amdhsa_exception_fp_ieee_div_zero 0
		.amdhsa_exception_fp_ieee_overflow 0
		.amdhsa_exception_fp_ieee_underflow 0
		.amdhsa_exception_fp_ieee_inexact 0
		.amdhsa_exception_int_div_zero 0
	.end_amdhsa_kernel

amdhsa.kernels:
  - .agpr_count:     0
    .args:
      - .offset:         0
        .size:           272
        .value_kind:     by_value
      - .offset:         272
        .size:           4
        .value_kind:     hidden_block_count_x
      - .offset:         276
        .size:           4
        .value_kind:     hidden_block_count_y
      - .offset:         280
        .size:           4
        .value_kind:     hidden_block_count_z
      - .offset:         284
        .size:           2
        .value_kind:     hidden_group_size_x
      - .offset:         286
        .size:           2
        .value_kind:     hidden_group_size_y
      - .offset:         288
        .size:           2
        .value_kind:     hidden_group_size_z
      - .offset:         290
        .size:           2
        .value_kind:     hidden_remainder_x
      - .offset:         292
        .size:           2
        .value_kind:     hidden_remainder_y
      - .offset:         294
        .size:           2
        .value_kind:     hidden_remainder_z
      - .offset:         312
        .size:           8
        .value_kind:     hidden_global_offset_x
      - .offset:         320
        .size:           8
        .value_kind:     hidden_global_offset_y
      - .offset:         328
        .size:           8
        .value_kind:     hidden_global_offset_z
      - .offset:         336
        .size:           2
        .value_kind:     hidden_grid_dims
      - .offset:         360
        .size:           8
        .value_kind:     hidden_multigrid_sync_arg
      - .offset:         392
        .size:           4
        .value_kind:     hidden_dynamic_lds_size
    .group_segment_fixed_size: 0
    .kernarg_segment_align: 8
    .kernarg_segment_size: 528
    .language:       OpenCL C
    .language_version:
      - 2
      - 0
    .max_flat_workgroup_size: 512
    .name:           _Z4mega6Params
    .private_segment_fixed_size: 0
    .sgpr_count:     106
    .sgpr_spill_count: 170
    .symbol:         _Z4mega6Params.kd
    .uniform_work_group_size: 1
    .uses_dynamic_stack: false
    .vgpr_count:     256
    .vgpr_spill_count: 0
    .wavefront_size: 64
